# attention exp2/pack/PV block re-emitted: MFMAs separated by next group's exps, V(kh1) frags prefetched, same math
# speedup vs baseline: 1.0204x; 1.0204x over previous
; #define MFMA(a, b, c) __builtin_amdgcn_mfma_f32_16x16x32_bf16((a), (b), (c), 0, 0, 0)
; template <int MODE> ...
;     ...
; #pragma unroll
;     for (int kh = 0; kh < 2; ++kh) {
; #pragma unroll
;       for (int tt = 0; tt < 2; ++tt) {
;         bf16x8 pf[2];
; #pragma unroll
;         for (int hh = 0; hh < 2; ++hh) {
;           float pv[8];
; #pragma unroll
;           for (int j = 0; j < 4; ++j) {
;             pv[j] = __builtin_amdgcn_exp2f(S[kh][tt][hh][0][j]);
;             pv[4 + j] = __builtin_amdgcn_exp2f(S[kh][tt][hh][1][j]);
;           }
;           lsum[tt][hh] += ((pv[0] + pv[1]) + (pv[2] + pv[3])) + ((pv[4] + pv[5]) + (pv[6] + pv[7]));
;           const uint4 pk = make_uint4(pack2(pv[0], pv[1]), pack2(pv[2], pv[3]), pack2(pv[4], pv[5]), pack2(pv[6], pv[7]));
;           pf[hh] = __builtin_bit_cast(bf16x8, pk);
;         }
; #pragma unroll
;         for (int dt = 0; dt < 4; ++dt) {
;           const bf16x8 vf = *(const bf16x8*)&Vs[(dt * 16 + r) * 64 + (((kh * 4 + g) ^ (r & 7)) * 8)];
;           O[tt][0][dt] = MFMA(vf, pf[0], O[tt][0][dt]);
;           O[tt][1][dt] = MFMA(vf, pf[1], O[tt][1][dt]);
;         }
;       }
;     }
.LBB0_873:
	ds_read_b128 v[120:123], v234 offset:8192
	ds_read_b128 v[116:119], v234 offset:10240
	ds_read_b128 v[112:115], v234 offset:12288
	ds_read_b128 v[108:111], v234 offset:14336
	v_exp_f32_e32 v208, v192
	v_exp_f32_e32 v212, v193
	v_exp_f32_e32 v216, v190
	v_exp_f32_e32 v220, v191
	v_exp_f32_e32 v209, v202
	v_exp_f32_e32 v213, v203
	v_exp_f32_e32 v217, v200
	v_exp_f32_e32 v221, v201
	v_exp_f32_e32 v210, v198
	v_exp_f32_e32 v214, v199
	v_exp_f32_e32 v218, v196
	v_exp_f32_e32 v222, v197
	v_exp_f32_e32 v211, v206
	v_exp_f32_e32 v215, v207
	v_exp_f32_e32 v219, v204
	v_exp_f32_e32 v223, v205
	v_pk_add_f32 v[248:249], v[212:213], v[208:209]
	v_pk_add_f32 v[250:251], v[220:221], v[216:217]
	v_pk_add_f32 v[248:249], v[250:251], v[248:249]
	v_pk_add_f32 v[250:251], v[214:215], v[210:211]
	v_pk_add_f32 v[252:253], v[222:223], v[218:219]
	v_pk_add_f32 v[250:251], v[252:253], v[250:251]
	v_pk_add_f32 v[248:249], v[250:251], v[248:249]
	v_pk_add_f32 v[188:189], v[248:249], v[188:189]
	v_cvt_pk_bf16_f32 v240, v208, v212
	v_cvt_pk_bf16_f32 v241, v216, v220
	v_cvt_pk_bf16_f32 v242, v210, v214
	v_cvt_pk_bf16_f32 v243, v218, v222
	v_cvt_pk_bf16_f32 v244, v209, v213
	v_cvt_pk_bf16_f32 v245, v217, v221
	v_cvt_pk_bf16_f32 v246, v211, v215
	v_cvt_pk_bf16_f32 v247, v219, v223
	ds_read_b128 v[208:211], v0 offset:8192
	ds_read_b128 v[212:215], v0 offset:10240
	ds_read_b128 v[216:219], v0 offset:12288
	ds_read_b128 v[220:223], v0 offset:14336
	s_mov_b64 s[42:43], 0
	s_waitcnt lgkmcnt(4)
	v_mfma_f32_16x16x32_bf16 v[52:55], v[120:123], v[240:243], v[52:55]
	v_exp_f32_e32 v200, v129
	v_mfma_f32_16x16x32_bf16 v[60:63], v[116:119], v[240:243], v[60:63]
	v_exp_f32_e32 v196, v125
	v_mfma_f32_16x16x32_bf16 v[56:59], v[112:115], v[240:243], v[56:59]
	v_exp_f32_e32 v198, v126
	v_mfma_f32_16x16x32_bf16 v[64:67], v[108:111], v[240:243], v[64:67]
	v_exp_f32_e32 v206, v131
	v_mfma_f32_16x16x32_bf16 v[44:47], v[120:123], v[244:247], v[44:47]
	v_exp_f32_e32 v204, v127
	v_mfma_f32_16x16x32_bf16 v[40:43], v[116:119], v[244:247], v[40:43]
	v_exp_f32_e32 v193, v134
	v_mfma_f32_16x16x32_bf16 v[36:39], v[112:115], v[244:247], v[36:39]
	v_exp_f32_e32 v191, v138
	v_mfma_f32_16x16x32_bf16 v[48:51], v[108:111], v[244:247], v[48:51]
	v_exp_f32_e32 v201, v135
	v_exp_f32_e32 v197, v139
	v_exp_f32_e32 v203, v132
	v_exp_f32_e32 v207, v133
	v_exp_f32_e32 v205, v137
	v_exp_f32_e32 v192, v128
	v_exp_f32_e32 v190, v124
	v_exp_f32_e32 v202, v130
	v_exp_f32_e32 v199, v136
	v_pk_add_f32 v[248:249], v[200:201], v[192:193]
	v_pk_add_f32 v[250:251], v[206:207], v[202:203]
	v_pk_add_f32 v[248:249], v[250:251], v[248:249]
	v_pk_add_f32 v[250:251], v[196:197], v[190:191]
	v_pk_add_f32 v[252:253], v[204:205], v[198:199]
	v_pk_add_f32 v[250:251], v[252:253], v[250:251]
	v_pk_add_f32 v[248:249], v[250:251], v[248:249]
	v_pk_add_f32 v[186:187], v[248:249], v[186:187]
	v_cvt_pk_bf16_f32 v240, v192, v200
	v_cvt_pk_bf16_f32 v241, v202, v206
	v_cvt_pk_bf16_f32 v242, v190, v196
	v_cvt_pk_bf16_f32 v243, v198, v204
	v_cvt_pk_bf16_f32 v244, v193, v201
	v_cvt_pk_bf16_f32 v245, v203, v207
	v_cvt_pk_bf16_f32 v246, v191, v197
	v_cvt_pk_bf16_f32 v247, v199, v205
	v_mfma_f32_16x16x32_bf16 v[20:23], v[108:111], v[240:243], v[20:23]
	v_exp_f32_e32 v126, v168
	v_mfma_f32_16x16x32_bf16 v[32:35], v[120:123], v[240:243], v[32:35]
	v_exp_f32_e32 v132, v169
	v_mfma_f32_16x16x32_bf16 v[28:31], v[116:119], v[240:243], v[28:31]
	v_exp_f32_e32 v134, v170
	v_mfma_f32_16x16x32_bf16 v[24:27], v[112:115], v[240:243], v[24:27]
	v_exp_f32_e32 v138, v171
	v_mfma_f32_16x16x32_bf16 v[4:7], v[108:111], v[244:247], v[4:7]
	v_exp_f32_e32 v127, v142
	v_mfma_f32_16x16x32_bf16 v[16:19], v[120:123], v[244:247], v[16:19]
	v_exp_f32_e32 v125, v146
	v_mfma_f32_16x16x32_bf16 v[12:15], v[116:119], v[244:247], v[12:15]
	v_exp_f32_e32 v133, v143
	v_mfma_f32_16x16x32_bf16 v[8:11], v[112:115], v[244:247], v[8:11]
	v_exp_f32_e32 v129, v147
	v_exp_f32_e32 v135, v140
	v_exp_f32_e32 v131, v144
	v_exp_f32_e32 v139, v141
	v_exp_f32_e32 v137, v145
	v_exp_f32_e32 v124, v164
	v_exp_f32_e32 v128, v165
	v_exp_f32_e32 v130, v166
	v_exp_f32_e32 v136, v167
	v_pk_add_f32 v[248:249], v[132:133], v[126:127]
	v_pk_add_f32 v[250:251], v[138:139], v[134:135]
	v_pk_add_f32 v[248:249], v[250:251], v[248:249]
	v_pk_add_f32 v[250:251], v[128:129], v[124:125]
	v_pk_add_f32 v[252:253], v[136:137], v[130:131]
	v_pk_add_f32 v[250:251], v[252:253], v[250:251]
	v_pk_add_f32 v[248:249], v[250:251], v[248:249]
	v_pk_add_f32 v[188:189], v[248:249], v[188:189]
	v_cvt_pk_bf16_f32 v240, v126, v132
	v_cvt_pk_bf16_f32 v241, v134, v138
	v_cvt_pk_bf16_f32 v242, v124, v128
	v_cvt_pk_bf16_f32 v243, v130, v136
	v_cvt_pk_bf16_f32 v244, v127, v133
	v_cvt_pk_bf16_f32 v245, v135, v139
	v_cvt_pk_bf16_f32 v246, v125, v129
	v_cvt_pk_bf16_f32 v247, v131, v137
	s_waitcnt lgkmcnt(0)
; #define MFMA(a, b, c) __builtin_amdgcn_mfma_f32_16x16x32_bf16((a), (b), (c), 0, 0, 0)
; template <int MODE> ...
;     ...
;         for (int hh = 0; hh < 2; ++hh) {
;           float pv[8];
; #pragma unroll
;           for (int j = 0; j < 4; ++j) {
;             pv[j] = __builtin_amdgcn_exp2f(S[kh][tt][hh][0][j]);
;             pv[4 + j] = __builtin_amdgcn_exp2f(S[kh][tt][hh][1][j]);
;           }
;           lsum[tt][hh] += ((pv[0] + pv[1]) + (pv[2] + pv[3])) + ((pv[4] + pv[5]) + (pv[6] + pv[7]));
;           const uint4 pk = make_uint4(pack2(pv[0], pv[1]), pack2(pv[2], pv[3]), pack2(pv[4], pv[5]), pack2(pv[6], pv[7]));
;           pf[hh] = __builtin_bit_cast(bf16x8, pk);
;         }
; #pragma unroll
;         for (int dt = 0; dt < 4; ++dt) {
;           const bf16x8 vf = *(const bf16x8*)&Vs[(dt * 16 + r) * 64 + (((kh * 4 + g) ^ (r & 7)) * 8)];
;           O[tt][0][dt] = MFMA(vf, pf[0], O[tt][0][dt]);
;           O[tt][1][dt] = MFMA(vf, pf[1], O[tt][1][dt]);
;         }
	v_mfma_f32_16x16x32_bf16 v[52:55], v[208:211], v[240:243], v[52:55]
	v_exp_f32_e32 v148, v148
	v_mfma_f32_16x16x32_bf16 v[60:63], v[212:215], v[240:243], v[60:63]
	v_exp_f32_e32 v146, v152
	v_mfma_f32_16x16x32_bf16 v[56:59], v[216:219], v[240:243], v[56:59]
	v_exp_f32_e32 v152, v153
	v_mfma_f32_16x16x32_bf16 v[64:67], v[220:223], v[240:243], v[64:67]
	v_exp_f32_e32 v145, v163
	v_mfma_f32_16x16x32_bf16 v[44:47], v[208:211], v[244:247], v[44:47]
	v_exp_f32_e32 v141, v162
	v_mfma_f32_16x16x32_bf16 v[40:43], v[212:215], v[244:247], v[40:43]
	v_exp_f32_e32 v147, v160
	v_mfma_f32_16x16x32_bf16 v[36:39], v[216:219], v[244:247], v[36:39]
	v_exp_f32_e32 v153, v161
	v_mfma_f32_16x16x32_bf16 v[48:51], v[220:223], v[244:247], v[48:51]
	v_exp_f32_e32 v142, v150
	v_exp_f32_e32 v140, v154
	v_exp_f32_e32 v150, v151
	v_exp_f32_e32 v144, v155
	v_exp_f32_e32 v154, v149
	v_exp_f32_e32 v143, v158
	v_exp_f32_e32 v151, v159
	v_exp_f32_e32 v149, v156
	v_exp_f32_e32 v155, v157
	v_pk_add_f32 v[248:249], v[150:151], v[142:143]
	v_pk_add_f32 v[250:251], v[154:155], v[148:149]
	v_pk_add_f32 v[248:249], v[250:251], v[248:249]
	v_pk_add_f32 v[250:251], v[144:145], v[140:141]
	v_pk_add_f32 v[252:253], v[152:153], v[146:147]
	v_pk_add_f32 v[250:251], v[252:253], v[250:251]
	v_pk_add_f32 v[248:249], v[250:251], v[248:249]
	v_pk_add_f32 v[186:187], v[248:249], v[186:187]
	v_cvt_pk_bf16_f32 v240, v142, v150
	v_cvt_pk_bf16_f32 v241, v148, v154
	v_cvt_pk_bf16_f32 v242, v140, v144
	v_cvt_pk_bf16_f32 v243, v146, v152
	v_cvt_pk_bf16_f32 v244, v143, v151
	v_cvt_pk_bf16_f32 v245, v149, v155
	v_cvt_pk_bf16_f32 v246, v141, v145
	v_cvt_pk_bf16_f32 v247, v147, v153
	v_mfma_f32_16x16x32_bf16 v[32:35], v[208:211], v[240:243], v[32:35]
	v_mfma_f32_16x16x32_bf16 v[28:31], v[212:215], v[240:243], v[28:31]
	v_mfma_f32_16x16x32_bf16 v[24:27], v[216:219], v[240:243], v[24:27]
	v_mfma_f32_16x16x32_bf16 v[20:23], v[220:223], v[240:243], v[20:23]
	v_mfma_f32_16x16x32_bf16 v[16:19], v[208:211], v[244:247], v[16:19]
	v_mfma_f32_16x16x32_bf16 v[12:15], v[212:215], v[244:247], v[12:15]
	v_mfma_f32_16x16x32_bf16 v[8:11], v[216:219], v[244:247], v[8:11]
	v_mfma_f32_16x16x32_bf16 v[4:7], v[220:223], v[244:247], v[4:7]
	s_andn2_b64 vcc, exec, s[56:57]
	s_cbranch_vccz .LBB0_867

; #define MFMA(a, b, c) __builtin_amdgcn_mfma_f32_16x16x32_bf16((a), (b), (c), 0, 0, 0)
; template <int MODE> ...
;     ...
;     for (int kh = 0; kh < 2; ++kh) {
; #pragma unroll
;       for (int tt = 0; tt < 2; ++tt) {
;         bf16x8 pf[2];
; #pragma unroll
;         for (int hh = 0; hh < 2; ++hh) {
;           float pv[8];
; #pragma unroll
;           for (int j = 0; j < 4; ++j) {
;             pv[j] = __builtin_amdgcn_exp2f(S[kh][tt][hh][0][j]);
;             pv[4 + j] = __builtin_amdgcn_exp2f(S[kh][tt][hh][1][j]);
;           }
;           lsum[tt][hh] += ((pv[0] + pv[1]) + (pv[2] + pv[3])) + ((pv[4] + pv[5]) + (pv[6] + pv[7]));
;           const uint4 pk = make_uint4(pack2(pv[0], pv[1]), pack2(pv[2], pv[3]), pack2(pv[4], pv[5]), pack2(pv[6], pv[7]));
;           pf[hh] = __builtin_bit_cast(bf16x8, pk);
;         }
; #pragma unroll
;         for (int dt = 0; dt < 4; ++dt) {
;           const bf16x8 vf = *(const bf16x8*)&Vs[(dt * 16 + r) * 64 + (((kh * 4 + g) ^ (r & 7)) * 8)];
;           O[tt][0][dt] = MFMA(vf, pf[0], O[tt][0][dt]);
;           O[tt][1][dt] = MFMA(vf, pf[1], O[tt][1][dt]);
;         }
;       }
;     }
.LBB0_893:
	ds_read_b128 v[102:105], v198 offset:8192
	ds_read_b128 v[98:101], v198 offset:10240
	ds_read_b128 v[94:97], v198 offset:12288
	ds_read_b128 v[90:93], v198 offset:14336
	v_exp_f32_e32 v200, v176
	v_exp_f32_e32 v204, v177
	v_exp_f32_e32 v208, v174
	v_exp_f32_e32 v212, v175
	v_exp_f32_e32 v201, v184
	v_exp_f32_e32 v205, v185
	v_exp_f32_e32 v209, v182
	v_exp_f32_e32 v213, v183
	v_exp_f32_e32 v202, v180
	v_exp_f32_e32 v206, v181
	v_exp_f32_e32 v210, v178
	v_exp_f32_e32 v214, v179
	v_exp_f32_e32 v203, v188
	v_exp_f32_e32 v207, v189
	v_exp_f32_e32 v211, v186
	v_exp_f32_e32 v215, v187
	v_pk_add_f32 v[248:249], v[204:205], v[200:201]
	v_pk_add_f32 v[250:251], v[212:213], v[208:209]
	v_pk_add_f32 v[248:249], v[250:251], v[248:249]
	v_pk_add_f32 v[250:251], v[206:207], v[202:203]
	v_pk_add_f32 v[252:253], v[214:215], v[210:211]
	v_pk_add_f32 v[250:251], v[252:253], v[250:251]
	v_pk_add_f32 v[248:249], v[250:251], v[248:249]
	v_pk_add_f32 v[170:171], v[248:249], v[170:171]
	v_cvt_pk_bf16_f32 v240, v200, v204
	v_cvt_pk_bf16_f32 v241, v208, v212
	v_cvt_pk_bf16_f32 v242, v202, v206
	v_cvt_pk_bf16_f32 v243, v210, v214
	v_cvt_pk_bf16_f32 v244, v201, v205
	v_cvt_pk_bf16_f32 v245, v209, v213
	v_cvt_pk_bf16_f32 v246, v203, v207
	v_cvt_pk_bf16_f32 v247, v211, v215
	ds_read_b128 v[200:203], v197 offset:8192
	ds_read_b128 v[204:207], v197 offset:10240
	ds_read_b128 v[208:211], v197 offset:12288
	ds_read_b128 v[212:215], v197 offset:14336
	s_mov_b64 s[42:43], 0
	s_waitcnt lgkmcnt(4)
	v_mfma_f32_16x16x32_bf16 v[70:73], v[102:105], v[240:243], v[70:73]
	v_exp_f32_e32 v176, v114
	v_mfma_f32_16x16x32_bf16 v[78:81], v[98:101], v[240:243], v[78:81]
	v_exp_f32_e32 v182, v115
	v_mfma_f32_16x16x32_bf16 v[62:65], v[94:97], v[240:243], v[62:65]
	v_exp_f32_e32 v178, v107
	v_mfma_f32_16x16x32_bf16 v[74:77], v[90:93], v[240:243], v[74:77]
	v_exp_f32_e32 v184, v116
	v_mfma_f32_16x16x32_bf16 v[86:89], v[102:105], v[244:247], v[86:89]
	v_exp_f32_e32 v180, v108
	v_mfma_f32_16x16x32_bf16 v[66:69], v[98:101], v[244:247], v[66:69]
	v_exp_f32_e32 v188, v117
	v_mfma_f32_16x16x32_bf16 v[58:61], v[94:97], v[244:247], v[58:61]
	v_exp_f32_e32 v186, v109
	v_mfma_f32_16x16x32_bf16 v[82:85], v[90:93], v[244:247], v[82:85]
	v_exp_f32_e32 v175, v120
	v_exp_f32_e32 v183, v113
	v_exp_f32_e32 v179, v121
	v_exp_f32_e32 v189, v111
	v_exp_f32_e32 v187, v119
	v_exp_f32_e32 v174, v106
	v_exp_f32_e32 v177, v112
	v_exp_f32_e32 v185, v110
	v_exp_f32_e32 v181, v118
	v_pk_add_f32 v[248:249], v[182:183], v[176:177]
	v_pk_add_f32 v[250:251], v[188:189], v[184:185]
	v_pk_add_f32 v[248:249], v[250:251], v[248:249]
	v_pk_add_f32 v[250:251], v[178:179], v[174:175]
	v_pk_add_f32 v[252:253], v[186:187], v[180:181]
	v_pk_add_f32 v[250:251], v[252:253], v[250:251]
	v_pk_add_f32 v[248:249], v[250:251], v[248:249]
	v_pk_add_f32 v[156:157], v[248:249], v[156:157]
	v_cvt_pk_bf16_f32 v240, v176, v182
	v_cvt_pk_bf16_f32 v241, v184, v188
	v_cvt_pk_bf16_f32 v242, v174, v178
	v_cvt_pk_bf16_f32 v243, v180, v186
	v_cvt_pk_bf16_f32 v244, v177, v183
	v_cvt_pk_bf16_f32 v245, v185, v189
	v_cvt_pk_bf16_f32 v246, v175, v179
	v_cvt_pk_bf16_f32 v247, v181, v187
	v_mfma_f32_16x16x32_bf16 v[6:9], v[90:93], v[240:243], v[6:9]
	v_exp_f32_e32 v108, v150
	v_mfma_f32_16x16x32_bf16 v[42:45], v[102:105], v[240:243], v[42:45]
	v_exp_f32_e32 v114, v151
	v_mfma_f32_16x16x32_bf16 v[34:37], v[98:101], v[240:243], v[34:37]
	v_exp_f32_e32 v116, v152
	v_mfma_f32_16x16x32_bf16 v[10:13], v[94:97], v[240:243], v[10:13]
	v_exp_f32_e32 v120, v153
	v_mfma_f32_16x16x32_bf16 v[2:5], v[90:93], v[244:247], v[2:5]
	v_exp_f32_e32 v109, v124
	v_mfma_f32_16x16x32_bf16 v[46:49], v[102:105], v[244:247], v[46:49]
	v_exp_f32_e32 v107, v128
	v_mfma_f32_16x16x32_bf16 v[38:41], v[98:101], v[244:247], v[38:41]
	v_exp_f32_e32 v115, v125
	v_mfma_f32_16x16x32_bf16 v[14:17], v[94:97], v[244:247], v[14:17]
	v_exp_f32_e32 v111, v129
	v_exp_f32_e32 v117, v122
	v_exp_f32_e32 v113, v126
	v_exp_f32_e32 v121, v123
	v_exp_f32_e32 v119, v127
	v_exp_f32_e32 v106, v146
	v_exp_f32_e32 v110, v147
	v_exp_f32_e32 v112, v148
	v_exp_f32_e32 v118, v149
	v_pk_add_f32 v[248:249], v[114:115], v[108:109]
	v_pk_add_f32 v[250:251], v[120:121], v[116:117]
	v_pk_add_f32 v[248:249], v[250:251], v[248:249]
	v_pk_add_f32 v[250:251], v[110:111], v[106:107]
	v_pk_add_f32 v[252:253], v[118:119], v[112:113]
	v_pk_add_f32 v[250:251], v[252:253], v[250:251]
	v_pk_add_f32 v[248:249], v[250:251], v[248:249]
	v_pk_add_f32 v[170:171], v[248:249], v[170:171]
	v_cvt_pk_bf16_f32 v240, v108, v114
	v_cvt_pk_bf16_f32 v241, v116, v120
	v_cvt_pk_bf16_f32 v242, v106, v110
	v_cvt_pk_bf16_f32 v243, v112, v118
	v_cvt_pk_bf16_f32 v244, v109, v115
	v_cvt_pk_bf16_f32 v245, v117, v121
	v_cvt_pk_bf16_f32 v246, v107, v111
	v_cvt_pk_bf16_f32 v247, v113, v119
	s_waitcnt lgkmcnt(0)
	v_mfma_f32_16x16x32_bf16 v[70:73], v[200:203], v[240:243], v[70:73]
	v_exp_f32_e32 v130, v130
	v_mfma_f32_16x16x32_bf16 v[78:81], v[204:207], v[240:243], v[78:81]
	v_exp_f32_e32 v128, v134
	v_mfma_f32_16x16x32_bf16 v[62:65], v[208:211], v[240:243], v[62:65]
	v_exp_f32_e32 v134, v135
	v_mfma_f32_16x16x32_bf16 v[74:77], v[212:215], v[240:243], v[74:77]
	v_exp_f32_e32 v127, v145
	v_mfma_f32_16x16x32_bf16 v[86:89], v[200:203], v[244:247], v[86:89]
	v_exp_f32_e32 v123, v144
	v_mfma_f32_16x16x32_bf16 v[66:69], v[204:207], v[244:247], v[66:69]
	v_exp_f32_e32 v129, v142
	v_mfma_f32_16x16x32_bf16 v[58:61], v[208:211], v[244:247], v[58:61]
	v_exp_f32_e32 v135, v143
	v_mfma_f32_16x16x32_bf16 v[82:85], v[212:215], v[244:247], v[82:85]
	v_exp_f32_e32 v124, v132
	v_exp_f32_e32 v122, v136
	v_exp_f32_e32 v132, v133
	v_exp_f32_e32 v126, v137
	v_exp_f32_e32 v136, v131
	v_exp_f32_e32 v125, v140
	v_exp_f32_e32 v133, v141
	v_exp_f32_e32 v131, v138
	v_exp_f32_e32 v137, v139
	v_pk_add_f32 v[248:249], v[132:133], v[124:125]
	v_pk_add_f32 v[250:251], v[136:137], v[130:131]
	v_pk_add_f32 v[248:249], v[250:251], v[248:249]
	v_pk_add_f32 v[250:251], v[126:127], v[122:123]
	v_pk_add_f32 v[252:253], v[134:135], v[128:129]
	v_pk_add_f32 v[250:251], v[252:253], v[250:251]
	v_pk_add_f32 v[248:249], v[250:251], v[248:249]
	v_pk_add_f32 v[156:157], v[248:249], v[156:157]
	v_cvt_pk_bf16_f32 v240, v124, v132
	v_cvt_pk_bf16_f32 v241, v130, v136
	v_cvt_pk_bf16_f32 v242, v122, v126
	v_cvt_pk_bf16_f32 v243, v128, v134
	v_cvt_pk_bf16_f32 v244, v125, v133
	v_cvt_pk_bf16_f32 v245, v131, v137
	v_cvt_pk_bf16_f32 v246, v123, v127
	v_cvt_pk_bf16_f32 v247, v129, v135
	v_mfma_f32_16x16x32_bf16 v[42:45], v[200:203], v[240:243], v[42:45]
	v_mfma_f32_16x16x32_bf16 v[34:37], v[204:207], v[240:243], v[34:37]
	v_mfma_f32_16x16x32_bf16 v[10:13], v[208:211], v[240:243], v[10:13]
	v_mfma_f32_16x16x32_bf16 v[6:9], v[212:215], v[240:243], v[6:9]
	v_mfma_f32_16x16x32_bf16 v[46:49], v[200:203], v[244:247], v[46:49]
	v_mfma_f32_16x16x32_bf16 v[38:41], v[204:207], v[244:247], v[38:41]
	v_mfma_f32_16x16x32_bf16 v[14:17], v[208:211], v[244:247], v[14:17]
	v_mfma_f32_16x16x32_bf16 v[2:5], v[212:215], v[244:247], v[2:5]
	s_andn2_b64 vcc, exec, s[48:49]
	s_cbranch_vccz .LBB0_887
